# mixA mlstmA + mixC: conv_unit loops de-serialised (weights hoisted, all row loads issued up front), CT fragment loads batched and reused
# speedup vs baseline: 1.0435x; 1.0165x over previous
; DI void conv_unit(const u16* __restrict__ PM, const float* __restrict__ conv_w, const float* __restrict__ conv_b, int b, int sl0, int ch, float scale, float* a8) {
;   { const float4 b0 = *(const float4*)(conv_b + ch), b1 = *(const float4*)(conv_b + ch + 4); a8[0] = b0.x; a8[1] = b0.y; a8[2] = b0.z; a8[3] = b0.w; a8[4] = b1.x; a8[5] = b1.y; a8[6] = b1.z; a8[7] = b1.w; }
; #pragma unroll
;   for (int j = 0; j < 4; ++j) {
;     const int sl = sl0 - 3 + j;
;     if (sl >= 0) {
;       const uint4 raw = *(const uint4*)(PM + ((size_t)b * SEQ + sl) * 1024 + ch);
;       float x8[8]; unpack8(raw, x8);
;       const float4 w0 = *(const float4*)(conv_w + j * 1024 + ch), w1 = *(const float4*)(conv_w + j * 1024 + ch + 4);
;       a8[0] += w0.x * x8[0]; a8[1] += w0.y * x8[1]; a8[2] += w0.z * x8[2]; a8[3] += w0.w * x8[3];
;       a8[4] += w1.x * x8[4]; a8[5] += w1.y * x8[5]; a8[6] += w1.z * x8[6]; a8[7] += w1.w * x8[7];
;     }
;   }
; DI void mlstmA_item(const Params& p, char* lds, int item) {
;     ...
;   for (int i = 0; i < 2; ++i) {
;     const int q = tid + 512 * i, e = q >> 3, s8 = (q & 7) * 8;
;     *(uint4*)(VTs + e * 72 + s8) = *(const uint4*)(VTm + ((size_t)(bh * 128 + e)) * SEQ + c * 64 + s8);
;   }
;   __syncthreads();
; #pragma unroll 1
;   for (int i = 0; i < 2; ++i) {
;     const int cgk = tid & 15, t = (tid >> 4) + 32 * i;
;     float a8[8];
;     conv_unit(PM, p.in[5], p.in[6], b, c * 64 + t, 512 + hd * 128 + cgk * 8, 0.08838834764831845f, a8);
.LBB0_330:
	s_or_b64 exec, exec, s[14:15]
	v_add_u32_e32 v4, 0x200, v18
	s_and_b32 s0, s10, 0xffffff80
	v_lshlrev_b32_e32 v2, 4, v18
	v_ashrrev_i32_e32 v9, 3, v18
	v_ashrrev_i32_e32 v14, 3, v4
	v_and_b32_e32 v16, 0x70, v2
	v_add_u32_e32 v2, s0, v9
	v_add_u32_e32 v4, s0, v14
	v_lshl_add_u64 v[0:1], v[0:1], 1, s[6:7]
	v_ashrrev_i32_e32 v3, 31, v2
	v_ashrrev_i32_e32 v5, 31, v4
	v_lshl_add_u64 v[0:1], v[0:1], 0, v[16:17]
	v_lshlrev_b64 v[2:3], 14, v[2:3]
	v_lshlrev_b64 v[4:5], 14, v[4:5]
	v_lshl_add_u64 v[2:3], v[0:1], 0, v[2:3]
	v_lshl_add_u64 v[4:5], v[0:1], 0, v[4:5]
	global_load_dwordx4 v[0:3], v[2:3], off
	s_nop 0
	global_load_dwordx4 v[4:7], v[4:5], off
	v_lshlrev_b32_e32 v8, 3, v18
	v_and_b32_e32 v22, 0x78, v8
	v_add_u32_e32 v8, 0, v16
	v_lshl_or_b32 v15, s27, 7, v22
	v_mad_u64_u32 v[12:13], s[0:1], v9, s26, v[8:9]
	v_lshlrev_b32_e32 v16, 2, v15
	v_mad_u64_u32 v[8:9], s[0:1], v14, s26, v[8:9]
	v_lshlrev_b64 v[10:11], 24, v[10:11]
	v_lshl_add_u64 v[10:11], s[4:5], 0, v[10:11]
	v_mov_b32_e32 v13, v17
	s_mov_b64 s[0:1], 0x1800
	v_ashrrev_i32_e32 v51, 4, v18
	v_mad_u32_u24 v52, v22, s26, 0
	s_mov_b32 s8, 0
	s_waitcnt vmcnt(1)
	ds_write_b128 v12, v[0:3] offset:18432
	s_waitcnt vmcnt(0)
	ds_write_b128 v8, v[4:7] offset:18432
	s_waitcnt lgkmcnt(0)
	s_barrier
	global_load_dwordx4 v[0:3], v16, s[64:65] offset:2064
	global_load_dwordx4 v[4:7], v16, s[64:65] offset:2048
	v_lshl_add_u64 v[8:9], s[62:63], 0, v[16:17]
	v_lshlrev_b32_e32 v12, 1, v15
	v_lshl_add_u64 v[10:11], v[10:11], 0, v[12:13]
	v_lshl_add_u64 v[12:13], v[8:9], 0, s[0:1]
	s_mov_b64 s[0:1], 0x2800
	v_lshl_add_u64 v[14:15], v[8:9], 0, s[0:1]
	s_mov_b64 s[0:1], 0x3800
	v_lshl_add_u64 v[20:21], v[8:9], 0, s[0:1]
	global_load_dwordx4 v[140:143], v[8:9], off offset:2048
	global_load_dwordx4 v[144:147], v[8:9], off offset:2064
	global_load_dwordx4 v[148:151], v[12:13], off
	global_load_dwordx4 v[152:155], v[12:13], off offset:16
	global_load_dwordx4 v[156:159], v[14:15], off
	global_load_dwordx4 v[160:163], v[14:15], off offset:16
	global_load_dwordx4 v[164:167], v[20:21], off
	global_load_dwordx4 v[168:171], v[20:21], off offset:16
	s_movk_i32 s8, 0x800
	v_add_u32_e32 v184, v51, v50
	v_add_u32_e32 v185, -1, v184
	v_mov_b32_e32 v114, 0
	v_mov_b32_e32 v115, 0
	v_mov_b32_e32 v116, 0
	v_mov_b32_e32 v117, 0
	v_mov_b32_e32 v118, 0
	v_mov_b32_e32 v119, 0
	v_mov_b32_e32 v120, 0
	v_mov_b32_e32 v121, 0
	v_mov_b32_e32 v122, 0
	v_mov_b32_e32 v123, 0
	v_mov_b32_e32 v124, 0
	v_mov_b32_e32 v125, 0
	v_mad_i64_i32 v[186:187], s[0:1], v185, s8, v[10:11]
	v_cmp_lt_i32_e64 s[0:1], 2, v184
	s_and_saveexec_b64 s[12:13], s[0:1]
	global_load_dwordx4 v[114:117], v[186:187], off offset:-3072
	s_or_b64 exec, exec, s[12:13]
	v_cmp_lt_i32_e64 s[0:1], 1, v184
	s_and_saveexec_b64 s[12:13], s[0:1]
	global_load_dwordx4 v[118:121], v[186:187], off offset:-1024
	s_or_b64 exec, exec, s[12:13]
	v_cmp_lt_i32_e64 s[0:1], 0, v184
	s_and_saveexec_b64 s[12:13], s[0:1]
	global_load_dwordx4 v[122:125], v[186:187], off offset:1024
	s_or_b64 exec, exec, s[12:13]
	global_load_dwordx4 v[126:129], v[186:187], off offset:3072
	v_add3_u32 v184, v51, v50, 32
	v_add_u32_e32 v185, -1, v184
	v_mov_b32_e32 v130, 0
	v_mov_b32_e32 v131, 0
	v_mov_b32_e32 v132, 0
	v_mov_b32_e32 v133, 0
	v_mov_b32_e32 v134, 0
	v_mov_b32_e32 v135, 0
	v_mov_b32_e32 v136, 0
	v_mov_b32_e32 v137, 0
	v_mov_b32_e32 v172, 0
	v_mov_b32_e32 v173, 0
	v_mov_b32_e32 v174, 0
	v_mov_b32_e32 v175, 0
	v_mad_i64_i32 v[186:187], s[0:1], v185, s8, v[10:11]
	v_cmp_lt_i32_e64 s[0:1], 2, v184
	s_and_saveexec_b64 s[12:13], s[0:1]
	global_load_dwordx4 v[130:133], v[186:187], off offset:-3072
	s_or_b64 exec, exec, s[12:13]
	v_cmp_lt_i32_e64 s[0:1], 1, v184
	s_and_saveexec_b64 s[12:13], s[0:1]
	global_load_dwordx4 v[134:137], v[186:187], off offset:-1024
	s_or_b64 exec, exec, s[12:13]
	v_cmp_lt_i32_e64 s[0:1], 0, v184
	s_and_saveexec_b64 s[12:13], s[0:1]
	global_load_dwordx4 v[172:175], v[186:187], off offset:1024
	s_or_b64 exec, exec, s[12:13]
	global_load_dwordx4 v[176:179], v[186:187], off offset:3072
	s_waitcnt vmcnt(4)
	v_mov_b32_e32 v197, v51
	v_lshlrev_b32_e32 v196, 2, v197
	ds_read_b32 v196, v196 offset:36864
	v_lshl_add_u32 v198, v197, 1, v52
	v_lshlrev_b32_e32 v188, 16, v114
	v_and_b32_e32 v189, 0xffff0000, v114
	v_lshlrev_b32_e32 v190, 16, v115
	v_and_b32_e32 v191, 0xffff0000, v115
	v_lshlrev_b32_e32 v192, 16, v116
	v_and_b32_e32 v193, 0xffff0000, v116
	v_lshlrev_b32_e32 v194, 16, v117
	v_and_b32_e32 v195, 0xffff0000, v117
	v_pk_fma_f32 v[204:205], v[140:141], v[188:189], v[4:5]
	v_pk_fma_f32 v[206:207], v[142:143], v[190:191], v[6:7]
	v_pk_fma_f32 v[208:209], v[144:145], v[192:193], v[0:1]
	v_pk_fma_f32 v[210:211], v[146:147], v[194:195], v[2:3]
	v_lshlrev_b32_e32 v188, 16, v118
	v_and_b32_e32 v189, 0xffff0000, v118
	v_lshlrev_b32_e32 v190, 16, v119
	v_and_b32_e32 v191, 0xffff0000, v119
	v_lshlrev_b32_e32 v192, 16, v120
	v_and_b32_e32 v193, 0xffff0000, v120
	v_lshlrev_b32_e32 v194, 16, v121
	v_and_b32_e32 v195, 0xffff0000, v121
	v_pk_fma_f32 v[204:205], v[148:149], v[188:189], v[204:205]
	v_pk_fma_f32 v[206:207], v[150:151], v[190:191], v[206:207]
	v_pk_fma_f32 v[208:209], v[152:153], v[192:193], v[208:209]
	v_pk_fma_f32 v[210:211], v[154:155], v[194:195], v[210:211]
	v_lshlrev_b32_e32 v188, 16, v122
	v_and_b32_e32 v189, 0xffff0000, v122
	v_lshlrev_b32_e32 v190, 16, v123
	v_and_b32_e32 v191, 0xffff0000, v123
	v_lshlrev_b32_e32 v192, 16, v124
	v_and_b32_e32 v193, 0xffff0000, v124
	v_lshlrev_b32_e32 v194, 16, v125
	v_and_b32_e32 v195, 0xffff0000, v125
	v_pk_fma_f32 v[204:205], v[156:157], v[188:189], v[204:205]
	v_pk_fma_f32 v[206:207], v[158:159], v[190:191], v[206:207]
; DI u16 f2bf(float x) { return (u16)(pack2(x, 0.f) & 0xffffu); }
; DI void conv_unit(const u16* __restrict__ PM, const float* __restrict__ conv_w, const float* __restrict__ conv_b, int b, int sl0, int ch, float scale, float* a8) {
;     ...
;   for (int e = 0; e < 8; ++e) { const float v = a8[e]; a8[e] = scale * v * __builtin_amdgcn_rcpf(1.f + __expf(-v)); }
; }
; DI void mlstmA_item(const Params& p, char* lds, int item) {
;     ...
;     const float w = win[t];
; #pragma unroll
;     for (int e = 0; e < 8; ++e) KTs[(cgk * 8 + e) * 72 + t] = f2bf(a8[e] * w);
	v_pk_fma_f32 v[208:209], v[160:161], v[192:193], v[208:209]
	v_pk_fma_f32 v[210:211], v[162:163], v[194:195], v[210:211]
	v_lshlrev_b32_e32 v188, 16, v126
	v_and_b32_e32 v189, 0xffff0000, v126
	v_lshlrev_b32_e32 v190, 16, v127
	v_and_b32_e32 v191, 0xffff0000, v127
	v_lshlrev_b32_e32 v192, 16, v128
	v_and_b32_e32 v193, 0xffff0000, v128
	v_lshlrev_b32_e32 v194, 16, v129
	v_and_b32_e32 v195, 0xffff0000, v129
	v_pk_fma_f32 v[204:205], v[164:165], v[188:189], v[204:205]
	v_pk_fma_f32 v[206:207], v[166:167], v[190:191], v[206:207]
	v_pk_fma_f32 v[208:209], v[168:169], v[192:193], v[208:209]
	v_pk_fma_f32 v[210:211], v[170:171], v[194:195], v[210:211]
	v_mul_f32_e32 v212, 0xbfb8aa3b, v204
	v_mul_f32_e32 v213, 0xbfb8aa3b, v205
	v_mul_f32_e32 v214, 0xbfb8aa3b, v206
	v_mul_f32_e32 v215, 0xbfb8aa3b, v207
	v_mul_f32_e32 v216, 0xbfb8aa3b, v208
	v_mul_f32_e32 v217, 0xbfb8aa3b, v209
	v_mul_f32_e32 v218, 0xbfb8aa3b, v210
	v_mul_f32_e32 v219, 0xbfb8aa3b, v211
	v_mul_f32_e32 v188, 0x3db504f3, v204
	v_mul_f32_e32 v189, 0x3db504f3, v205
	v_mul_f32_e32 v190, 0x3db504f3, v206
	v_mul_f32_e32 v191, 0x3db504f3, v207
	v_mul_f32_e32 v192, 0x3db504f3, v208
	v_mul_f32_e32 v193, 0x3db504f3, v209
	v_mul_f32_e32 v194, 0x3db504f3, v210
	v_mul_f32_e32 v195, 0x3db504f3, v211
	v_exp_f32_e32 v212, v212
	v_exp_f32_e32 v213, v213
	v_exp_f32_e32 v214, v214
	v_exp_f32_e32 v215, v215
	v_exp_f32_e32 v216, v216
	v_exp_f32_e32 v217, v217
	v_exp_f32_e32 v218, v218
	v_exp_f32_e32 v219, v219
	v_add_f32_e32 v212, 1.0, v212
	v_add_f32_e32 v213, 1.0, v213
	v_add_f32_e32 v214, 1.0, v214
	v_add_f32_e32 v215, 1.0, v215
	v_add_f32_e32 v216, 1.0, v216
	v_add_f32_e32 v217, 1.0, v217
	v_add_f32_e32 v218, 1.0, v218
	v_add_f32_e32 v219, 1.0, v219
	v_rcp_f32_e32 v212, v212
	v_rcp_f32_e32 v213, v213
	v_rcp_f32_e32 v214, v214
	v_rcp_f32_e32 v215, v215
	v_rcp_f32_e32 v216, v216
	v_rcp_f32_e32 v217, v217
	v_rcp_f32_e32 v218, v218
	v_rcp_f32_e32 v219, v219
	v_mul_f32_e32 v188, v188, v212
	v_mul_f32_e32 v189, v189, v213
	v_mul_f32_e32 v190, v190, v214
	v_mul_f32_e32 v191, v191, v215
	v_mul_f32_e32 v192, v192, v216
	v_mul_f32_e32 v193, v193, v217
	v_mul_f32_e32 v194, v194, v218
	v_mul_f32_e32 v195, v195, v219
	s_waitcnt lgkmcnt(0)
	v_mul_f32_e32 v188, v196, v188
	v_mul_f32_e32 v189, v196, v189
	v_mul_f32_e32 v190, v196, v190
	v_mul_f32_e32 v191, v196, v191
	v_mul_f32_e32 v192, v196, v192
	v_mul_f32_e32 v193, v193, v196
	v_mul_f32_e32 v194, v194, v196
	v_mul_f32_e32 v195, v195, v196
	v_cvt_pk_bf16_f32 v188, v188, s0
	v_cvt_pk_bf16_f32 v189, v189, s0
	v_cvt_pk_bf16_f32 v190, v190, s0
	v_cvt_pk_bf16_f32 v191, v191, s0
	v_cvt_pk_bf16_f32 v192, v192, s0
	v_cvt_pk_bf16_f32 v193, v193, s0
	v_cvt_pk_bf16_f32 v194, v194, s0
	v_cvt_pk_bf16_f32 v195, v195, s0
	ds_write_b16 v198, v188
	ds_write_b16 v198, v189 offset:144
	ds_write_b16 v198, v190 offset:288
	ds_write_b16 v198, v191 offset:432
	ds_write_b16 v198, v192 offset:576
	ds_write_b16 v198, v193 offset:720
	ds_write_b16 v198, v194 offset:864
	ds_write_b16 v198, v195 offset:1008
	s_waitcnt vmcnt(0)
; DI u16 f2bf(float x) { return (u16)(pack2(x, 0.f) & 0xffffu); }
; DI void conv_unit(const u16* __restrict__ PM, const float* __restrict__ conv_w, const float* __restrict__ conv_b, int b, int sl0, int ch, float scale, float* a8) {
;   { const float4 b0 = *(const float4*)(conv_b + ch), b1 = *(const float4*)(conv_b + ch + 4); a8[0] = b0.x; a8[1] = b0.y; a8[2] = b0.z; a8[3] = b0.w; a8[4] = b1.x; a8[5] = b1.y; a8[6] = b1.z; a8[7] = b1.w; }
; #pragma unroll
;   for (int j = 0; j < 4; ++j) {
;     const int sl = sl0 - 3 + j;
;     if (sl >= 0) {
;       const uint4 raw = *(const uint4*)(PM + ((size_t)b * SEQ + sl) * 1024 + ch);
;       float x8[8]; unpack8(raw, x8);
;       const float4 w0 = *(const float4*)(conv_w + j * 1024 + ch), w1 = *(const float4*)(conv_w + j * 1024 + ch + 4);
;       a8[0] += w0.x * x8[0]; a8[1] += w0.y * x8[1]; a8[2] += w0.z * x8[2]; a8[3] += w0.w * x8[3];
;       a8[4] += w1.x * x8[4]; a8[5] += w1.y * x8[5]; a8[6] += w1.z * x8[6]; a8[7] += w1.w * x8[7];
;     }
;   }
; #pragma unroll
;   for (int e = 0; e < 8; ++e) { const float v = a8[e]; a8[e] = scale * v * __builtin_amdgcn_rcpf(1.f + __expf(-v)); }
; }
; DI void mlstmA_item(const Params& p, char* lds, int item) {
;     ...
;     const int cgk = tid & 15, t = (tid >> 4) + 32 * i;
;     float a8[8];
;     conv_unit(PM, p.in[5], p.in[6], b, c * 64 + t, 512 + hd * 128 + cgk * 8, 0.08838834764831845f, a8);
;     const float w = win[t];
; #pragma unroll
;     for (int e = 0; e < 8; ++e) KTs[(cgk * 8 + e) * 72 + t] = f2bf(a8[e] * w);
	v_add_u32_e32 v197, 32, v51
	v_lshlrev_b32_e32 v196, 2, v197
	ds_read_b32 v196, v196 offset:36864
	v_lshl_add_u32 v198, v197, 1, v52
	v_lshlrev_b32_e32 v188, 16, v130
	v_and_b32_e32 v189, 0xffff0000, v130
	v_lshlrev_b32_e32 v190, 16, v131
	v_and_b32_e32 v191, 0xffff0000, v131
	v_lshlrev_b32_e32 v192, 16, v132
	v_and_b32_e32 v193, 0xffff0000, v132
	v_lshlrev_b32_e32 v194, 16, v133
	v_and_b32_e32 v195, 0xffff0000, v133
	v_pk_fma_f32 v[204:205], v[140:141], v[188:189], v[4:5]
	v_pk_fma_f32 v[206:207], v[142:143], v[190:191], v[6:7]
	v_pk_fma_f32 v[208:209], v[144:145], v[192:193], v[0:1]
	v_pk_fma_f32 v[210:211], v[146:147], v[194:195], v[2:3]
	v_lshlrev_b32_e32 v188, 16, v134
	v_and_b32_e32 v189, 0xffff0000, v134
	v_lshlrev_b32_e32 v190, 16, v135
	v_and_b32_e32 v191, 0xffff0000, v135
	v_lshlrev_b32_e32 v192, 16, v136
	v_and_b32_e32 v193, 0xffff0000, v136
	v_lshlrev_b32_e32 v194, 16, v137
	v_and_b32_e32 v195, 0xffff0000, v137
	v_pk_fma_f32 v[204:205], v[148:149], v[188:189], v[204:205]
	v_pk_fma_f32 v[206:207], v[150:151], v[190:191], v[206:207]
	v_pk_fma_f32 v[208:209], v[152:153], v[192:193], v[208:209]
	v_pk_fma_f32 v[210:211], v[154:155], v[194:195], v[210:211]
	v_lshlrev_b32_e32 v188, 16, v172
	v_and_b32_e32 v189, 0xffff0000, v172
	v_lshlrev_b32_e32 v190, 16, v173
	v_and_b32_e32 v191, 0xffff0000, v173
	v_lshlrev_b32_e32 v192, 16, v174
	v_and_b32_e32 v193, 0xffff0000, v174
	v_lshlrev_b32_e32 v194, 16, v175
	v_and_b32_e32 v195, 0xffff0000, v175
	v_pk_fma_f32 v[204:205], v[156:157], v[188:189], v[204:205]
	v_pk_fma_f32 v[206:207], v[158:159], v[190:191], v[206:207]
	v_pk_fma_f32 v[208:209], v[160:161], v[192:193], v[208:209]
	v_pk_fma_f32 v[210:211], v[162:163], v[194:195], v[210:211]
	v_lshlrev_b32_e32 v188, 16, v176
	v_and_b32_e32 v189, 0xffff0000, v176
	v_lshlrev_b32_e32 v190, 16, v177
	v_and_b32_e32 v191, 0xffff0000, v177
	v_lshlrev_b32_e32 v192, 16, v178
	v_and_b32_e32 v193, 0xffff0000, v178
	v_lshlrev_b32_e32 v194, 16, v179
	v_and_b32_e32 v195, 0xffff0000, v179
	v_pk_fma_f32 v[204:205], v[164:165], v[188:189], v[204:205]
	v_pk_fma_f32 v[206:207], v[166:167], v[190:191], v[206:207]
	v_pk_fma_f32 v[208:209], v[168:169], v[192:193], v[208:209]
	v_pk_fma_f32 v[210:211], v[170:171], v[194:195], v[210:211]
	v_mul_f32_e32 v212, 0xbfb8aa3b, v204
	v_mul_f32_e32 v213, 0xbfb8aa3b, v205
	v_mul_f32_e32 v214, 0xbfb8aa3b, v206
	v_mul_f32_e32 v215, 0xbfb8aa3b, v207
	v_mul_f32_e32 v216, 0xbfb8aa3b, v208
	v_mul_f32_e32 v217, 0xbfb8aa3b, v209
	v_mul_f32_e32 v218, 0xbfb8aa3b, v210
	v_mul_f32_e32 v219, 0xbfb8aa3b, v211
	v_mul_f32_e32 v188, 0x3db504f3, v204
	v_mul_f32_e32 v189, 0x3db504f3, v205
	v_mul_f32_e32 v190, 0x3db504f3, v206
	v_mul_f32_e32 v191, 0x3db504f3, v207
	v_mul_f32_e32 v192, 0x3db504f3, v208
	v_mul_f32_e32 v193, 0x3db504f3, v209
	v_mul_f32_e32 v194, 0x3db504f3, v210
	v_mul_f32_e32 v195, 0x3db504f3, v211
	v_exp_f32_e32 v212, v212
	v_exp_f32_e32 v213, v213
	v_exp_f32_e32 v214, v214
	v_exp_f32_e32 v215, v215
	v_exp_f32_e32 v216, v216
	v_exp_f32_e32 v217, v217
	v_exp_f32_e32 v218, v218
	v_exp_f32_e32 v219, v219
	v_add_f32_e32 v212, 1.0, v212
	v_add_f32_e32 v213, 1.0, v213
	v_add_f32_e32 v214, 1.0, v214
	v_add_f32_e32 v215, 1.0, v215
	v_add_f32_e32 v216, 1.0, v216
	v_add_f32_e32 v217, 1.0, v217
	v_add_f32_e32 v218, 1.0, v218
	v_add_f32_e32 v219, 1.0, v219
	v_rcp_f32_e32 v212, v212
	v_rcp_f32_e32 v213, v213
	v_rcp_f32_e32 v214, v214
	v_rcp_f32_e32 v215, v215
	v_rcp_f32_e32 v216, v216
	v_rcp_f32_e32 v217, v217
	v_rcp_f32_e32 v218, v218
	v_rcp_f32_e32 v219, v219
	v_mul_f32_e32 v188, v188, v212
	v_mul_f32_e32 v189, v189, v213
	v_mul_f32_e32 v190, v190, v214
	v_mul_f32_e32 v191, v191, v215
	v_mul_f32_e32 v192, v192, v216
	v_mul_f32_e32 v193, v193, v217
	v_mul_f32_e32 v194, v194, v218
	v_mul_f32_e32 v195, v195, v219
	s_waitcnt lgkmcnt(0)
	v_mul_f32_e32 v188, v196, v188
	v_mul_f32_e32 v189, v196, v189
	v_mul_f32_e32 v190, v196, v190
	v_mul_f32_e32 v191, v196, v191
	v_mul_f32_e32 v192, v196, v192
	v_mul_f32_e32 v193, v193, v196
	v_mul_f32_e32 v194, v194, v196
	v_mul_f32_e32 v195, v195, v196
	v_cvt_pk_bf16_f32 v188, v188, s0
	v_cvt_pk_bf16_f32 v189, v189, s0
	v_cvt_pk_bf16_f32 v190, v190, s0
	v_cvt_pk_bf16_f32 v191, v191, s0
	v_cvt_pk_bf16_f32 v192, v192, s0
	v_cvt_pk_bf16_f32 v193, v193, s0
	v_cvt_pk_bf16_f32 v194, v194, s0
	v_cvt_pk_bf16_f32 v195, v195, s0
	ds_write_b16 v198, v188
	ds_write_b16 v198, v189 offset:144
	ds_write_b16 v198, v190 offset:288
	ds_write_b16 v198, v191 offset:432
	ds_write_b16 v198, v192 offset:576
	ds_write_b16 v198, v193 offset:720
	ds_write_b16 v198, v194 offset:864
	ds_write_b16 v198, v195 offset:1008

; #define MFMA(a, b, c) __builtin_amdgcn_mfma_f32_32x32x16_bf16((a), (b), (c), 0, 0, 0)
; DI f32x16 zero16() { f32x16 z; for (int i = 0; i < 16; ++i) z[i] = 0.f; return z; }
; DI void mlstmC_pair(const Params& p, char* lds_all, int pair) {
;     ...
;   for (int tt = 0; tt < 2; ++tt) {
;     const int tq = tt * 32 + l31;
;     Hn[tt] = zero16();
;     if (c > 0) {
; #pragma unroll
;       for (int kk = 0; kk < 8; ++kk) Hn[tt] = MFMA(ldfrag(CT + (et * 32 + l31) * 128 + kk * 16 + 8 * hh), ldfrag(Qs + tq * 136 + kk * 16 + 8 * hh), Hn[tt]);
;     }
.LBB0_618:
	s_or_b64 exec, exec, s[4:5]
	s_waitcnt lgkmcnt(1)
	v_lshlrev_b64 v[2:3], 15, v[24:25]
	v_lshlrev_b32_e32 v0, 8, v53
	v_lshl_add_u64 v[2:3], s[58:59], 0, v[2:3]
	v_lshl_or_b32 v20, v28, 13, v0
	v_lshlrev_b32_e32 v18, 1, v1
	v_lshl_add_u64 v[0:1], v[2:3], 0, v[20:21]
	v_mov_b32_e32 v19, v21
	v_add_u32_e32 v29, v51, v18
	v_lshl_add_u64 v[16:17], v[0:1], 0, v[18:19]
	v_mov_b32_e32 v0, 0
	v_mov_b32_e32 v1, 0
	v_mov_b32_e32 v2, 0
	v_mov_b32_e32 v3, 0
	v_mov_b32_e32 v4, 0
	v_mov_b32_e32 v5, 0
	v_mov_b32_e32 v6, 0
	v_mov_b32_e32 v7, 0
	v_mov_b32_e32 v8, 0
	v_mov_b32_e32 v9, 0
	v_mov_b32_e32 v10, 0
	v_mov_b32_e32 v11, 0
	v_mov_b32_e32 v12, 0
	v_mov_b32_e32 v13, 0
	v_mov_b32_e32 v14, 0
	v_mov_b32_e32 v15, 0
	s_waitcnt lgkmcnt(0)
	s_barrier
	s_and_saveexec_b64 s[4:5], vcc
	s_cbranch_execz .LBB0_620
	global_load_dwordx4 v[118:121], v[16:17], off
	global_load_dwordx4 v[122:125], v[16:17], off offset:32
	global_load_dwordx4 v[126:129], v[16:17], off offset:64
	global_load_dwordx4 v[130:133], v[16:17], off offset:96
	global_load_dwordx4 v[134:137], v[16:17], off offset:128
	global_load_dwordx4 v[138:141], v[16:17], off offset:160
	global_load_dwordx4 v[142:145], v[16:17], off offset:192
	global_load_dwordx4 v[146:149], v[16:17], off offset:224
	v_mad_u32_u24 v19, v53, s18, v29
	ds_read_b128 v[150:153], v19
	ds_read_b128 v[154:157], v19 offset:32
	ds_read_b128 v[158:161], v19 offset:64
	ds_read_b128 v[162:165], v19 offset:96
	ds_read_b128 v[166:169], v19 offset:128
	ds_read_b128 v[170:173], v19 offset:160
	ds_read_b128 v[174:177], v19 offset:192
	ds_read_b128 v[178:181], v19 offset:224
	s_waitcnt vmcnt(7) lgkmcnt(7)
	v_mfma_f32_32x32x16_bf16 v[0:15], v[118:121], v[150:153], 0
	s_waitcnt vmcnt(6) lgkmcnt(6)
	v_mfma_f32_32x32x16_bf16 v[0:15], v[122:125], v[154:157], v[0:15]
	s_waitcnt vmcnt(5) lgkmcnt(5)
	v_mfma_f32_32x32x16_bf16 v[0:15], v[126:129], v[158:161], v[0:15]
	s_waitcnt vmcnt(4) lgkmcnt(4)
	v_mfma_f32_32x32x16_bf16 v[0:15], v[130:133], v[162:165], v[0:15]
	s_waitcnt vmcnt(3) lgkmcnt(3)
	v_mfma_f32_32x32x16_bf16 v[0:15], v[134:137], v[166:169], v[0:15]
	s_waitcnt vmcnt(2) lgkmcnt(2)
	v_mfma_f32_32x32x16_bf16 v[0:15], v[138:141], v[170:173], v[0:15]
	s_waitcnt vmcnt(1) lgkmcnt(1)
	v_mfma_f32_32x32x16_bf16 v[0:15], v[142:145], v[174:177], v[0:15]
	s_waitcnt vmcnt(0) lgkmcnt(0)
	v_mfma_f32_32x32x16_bf16 v[0:15], v[146:149], v[178:181], v[0:15]

; #define MFMA(a, b, c) __builtin_amdgcn_mfma_f32_32x32x16_bf16((a), (b), (c), 0, 0, 0)
; DI f32x16 zero16() { f32x16 z; for (int i = 0; i < 16; ++i) z[i] = 0.f; return z; }
; DI void mlstmC_pair(const Params& p, char* lds_all, int pair) {
;     ...
;   for (int tt = 0; tt < 2; ++tt) {
;     const int tq = tt * 32 + l31;
;     Hn[tt] = zero16();
;     if (c > 0) {
; #pragma unroll
;       for (int kk = 0; kk < 8; ++kk) Hn[tt] = MFMA(ldfrag(CT + (et * 32 + l31) * 128 + kk * 16 + 8 * hh), ldfrag(Qs + tq * 136 + kk * 16 + 8 * hh), Hn[tt]);
;     }
.LBB0_622:
	s_or_b64 exec, exec, s[4:5]
	v_or_b32_e32 v52, 32, v53
	v_mov_b32_e32 v0, 0
	v_mov_b32_e32 v1, 0
	s_waitcnt lgkmcnt(1)
	v_mov_b32_e32 v2, 0
	s_waitcnt lgkmcnt(0)
	v_mov_b32_e32 v3, 0
	v_mov_b32_e32 v4, 0
	v_mov_b32_e32 v5, 0
	v_mov_b32_e32 v6, 0
	v_mov_b32_e32 v7, 0
	v_mov_b32_e32 v8, 0
	v_mov_b32_e32 v9, 0
	v_mov_b32_e32 v10, 0
	v_mov_b32_e32 v11, 0
	v_mov_b32_e32 v12, 0
	v_mov_b32_e32 v13, 0
	v_mov_b32_e32 v14, 0
	v_mov_b32_e32 v15, 0
	s_and_saveexec_b64 s[4:5], vcc
	s_cbranch_execz .LBB0_624
	v_mad_u32_u24 v20, v52, s18, v29
	ds_read_b128 v[150:153], v20
	ds_read_b128 v[154:157], v20 offset:32
	ds_read_b128 v[158:161], v20 offset:64
	ds_read_b128 v[162:165], v20 offset:96
	ds_read_b128 v[166:169], v20 offset:128
	ds_read_b128 v[170:173], v20 offset:160
	ds_read_b128 v[174:177], v20 offset:192
	ds_read_b128 v[178:181], v20 offset:224
	s_waitcnt lgkmcnt(7)
	v_mfma_f32_32x32x16_bf16 v[0:15], v[118:121], v[150:153], 0
	s_waitcnt lgkmcnt(6)
	v_mfma_f32_32x32x16_bf16 v[0:15], v[122:125], v[154:157], v[0:15]
	s_waitcnt lgkmcnt(5)
	v_mfma_f32_32x32x16_bf16 v[0:15], v[126:129], v[158:161], v[0:15]
	s_waitcnt lgkmcnt(4)
	v_mfma_f32_32x32x16_bf16 v[0:15], v[130:133], v[162:165], v[0:15]
	s_waitcnt lgkmcnt(3)
	v_mfma_f32_32x32x16_bf16 v[0:15], v[134:137], v[166:169], v[0:15]
	s_waitcnt lgkmcnt(2)
	v_mfma_f32_32x32x16_bf16 v[0:15], v[138:141], v[170:173], v[0:15]
	s_waitcnt lgkmcnt(1)
	v_mfma_f32_32x32x16_bf16 v[0:15], v[142:145], v[174:177], v[0:15]
	s_waitcnt lgkmcnt(0)
	v_mfma_f32_32x32x16_bf16 v[0:15], v[146:149], v[178:181], v[0:15]
